# v070 stack + RG unit per-direction prologue: first xc tile LDS-DMA before the gate-weight wait; ctx attention prologue: first K/V tile DMA before the Q ladder
# speedup vs baseline: 1.0045x; 1.0045x over previous
.LBB0_745:
	s_andn2_b64 vcc, exec, s[4:5]
	s_cbranch_vccnz .LBB0_782
	s_andn2_b64 vcc, exec, s[82:83]
	s_cbranch_vccnz .LBB0_782
	s_lshl_b32 s0, s22, 6
	s_and_b32 s0, s0, 0xf00
	v_mbcnt_lo_u32_b32 v0, -1, 0
	v_mbcnt_hi_u32_b32 v0, -1, v0
	s_or_b32 s3, s0, 0x8000
	v_add_u32_e32 v38, s93, v0
	v_readlane_b32 s10, v255, 11
	v_readfirstlane_b32 s0, v38
	s_ashr_i32 s2, s0, 6
	s_lshl_b32 s0, s2, 5
	v_and_b32_e32 v34, 31, v38
	s_add_i32 s0, s0, s3
	v_readlane_b32 s11, v255, 12
	s_and_b32 s1, s22, 3
	v_or_b32_e32 v0, s0, v34
	v_mov_b64_e32 v[2:3], s[10:11]
	v_bfe_u32 v35, v38, 5, 1
	v_mad_i64_i32 v[2:3], s[4:5], v0, s72, v[2:3]
	s_lshl_b32 s36, s1, 8
	v_lshl_add_u64 v[2:3], v[2:3], 0, s[36:37]
	v_lshlrev_b32_e32 v0, 4, v35
	v_lshl_add_u64 v[30:31], v[2:3], 0, v[0:1]
	global_load_dwordx4 v[2:5], v[30:31], off offset:2560
	global_load_dwordx4 v[6:9], v[30:31], off offset:2592
	global_load_dwordx4 v[10:13], v[30:31], off offset:2624
	global_load_dwordx4 v[14:17], v[30:31], off offset:2656
	global_load_dwordx4 v[18:21], v[30:31], off offset:2688
	global_load_dwordx4 v[22:25], v[30:31], off offset:2720
	global_load_dwordx4 v[26:29], v[30:31], off offset:2752
	s_nop 0
	global_load_dwordx4 v[30:33], v[30:31], off offset:2784
	v_lshlrev_b32_e32 v39, 4, v38
	v_and_b32_e32 v43, 0xf0, v39
	s_movk_i32 s6, 0x60
	v_bitop3_b32 v217, v0, v43, s6 bitop3:0x36
	s_movk_i32 s6, 0x80
	v_bitop3_b32 v218, v0, v43, s6 bitop3:0x36
	s_movk_i32 s6, 0xa0
	v_bitop3_b32 v219, v0, v43, s6 bitop3:0x36
	s_movk_i32 s6, 0xc0
	v_lshlrev_b32_e32 v42, 3, v38
	s_lshl_b32 s4, s2, 9
	s_lshl_b32 s5, s2, 13
	v_bitop3_b32 v220, v0, v43, s6 bitop3:0x36
	s_movk_i32 s6, 0xe0
	v_bfe_u32 v40, v38, 4, 2
	v_lshlrev_b32_e32 v214, 8, v34
	v_bitop3_b32 v34, v35, v38, 15 bitop3:0x78
	v_and_b32_e32 v35, 24, v42
	v_bitop3_b32 v221, v0, v43, s6 bitop3:0x36
	s_lshl_b32 s6, s2, 3
	s_add_i32 s15, s5, 0
	s_add_i32 s14, s4, 0
	s_lshl_b32 s1, s1, 7
	v_and_or_b32 v46, v38, 32, v35
	v_or_b32_e32 v35, s6, v40
	s_add_i32 s15, s15, 0x11000
	s_add_i32 s14, s14, 0x10000
	s_movk_i32 s8, 0xb00
	v_bfe_u32 v41, v38, 2, 3
	v_bitop3_b32 v37, s6, v38, v40 bitop3:0x36
	v_mul_lo_u32 v47, v35, s8
	v_bitop3_b32 v35, v35, v38, 4 bitop3:0x36
	s_add_u32 s4, s10, s36
	s_mulk_i32 s3, 0x1600
	v_or_b32_e32 v36, s6, v41
	v_lshlrev_b32_e32 v37, 3, v37
	v_lshlrev_b32_e32 v35, 3, v35
	s_addc_u32 s5, s11, 0
	v_mul_lo_u32 v36, v36, s8
	v_add_u32_e32 v48, s15, v214
	v_and_b32_e32 v49, 0x78, v37
	v_and_b32_e32 v57, 0x78, v35
	s_add_u32 s4, s4, s3
	v_or_b32_e32 v36, v36, v46
	v_lshl_add_u32 v37, v34, 4, v48
	v_or_b32_e32 v34, v49, v47
	v_or_b32_e32 v35, v47, v57
	s_addc_u32 s5, s5, 0
	s_lshl_b32 s3, s2, 11
	v_bitop3_b32 v215, v0, v43, 32 bitop3:0x36
	v_bitop3_b32 v216, v0, v43, 64 bitop3:0x36
	v_lshlrev_b32_e32 v56, 1, v36
	v_lshlrev_b32_e32 v34, 1, v34
	v_lshl_add_u32 v36, v35, 1, v249
	s_add_u32 s6, s4, 0x1200
	v_mov_b32_e32 v35, v1
	v_add_u32_e32 v50, v48, v215
	v_add_u32_e32 v51, v48, v216
	v_add_u32_e32 v52, v48, v217
	v_add_u32_e32 v53, v48, v218
	v_add_u32_e32 v54, v48, v219
	v_add_u32_e32 v55, v48, v220
	v_add_u32_e32 v48, v48, v221
	s_addc_u32 s7, s5, 0
	s_add_i32 s38, s3, 0
	s_add_i32 m0, s38, 0x8000
	v_lshl_add_u64 v[58:59], s[4:5], 0, v[34:35]
	v_lshl_add_u64 v[58:59], v[58:59], 0, s[26:27]
	global_load_lds_dwordx4 v[58:59], off
	s_mov_b32 m0, s38
	v_mov_b32_e32 v60, v36
	v_mov_b32_e32 v61, v1
	v_lshl_add_u64 v[58:59], s[4:5], 0, v[60:61]
	global_load_lds_dwordx4 v56, s[6:7]
	v_lshl_add_u64 v[58:59], v[58:59], 0, s[26:27]
	s_add_i32 m0, s38, 0x8400
	v_or_b32_e32 v47, 0x80, v56
	global_load_lds_dwordx4 v[58:59], off
	s_add_i32 m0, s38, 0x400
	s_nop 0
	global_load_lds_dwordx4 v47, s[6:7]
	s_waitcnt vmcnt(11)
	ds_write_b128 v37, v[2:5]
	s_waitcnt vmcnt(10)
	ds_write_b128 v50, v[6:9]
	s_waitcnt vmcnt(9)
	ds_write_b128 v51, v[10:13]
	s_waitcnt vmcnt(8)
	ds_write_b128 v52, v[14:17]
	s_waitcnt vmcnt(7)
	ds_write_b128 v53, v[18:21]
	s_waitcnt vmcnt(6)
	ds_write_b128 v54, v[22:25]
	s_waitcnt vmcnt(5)
	ds_write_b128 v55, v[26:29]
	s_waitcnt vmcnt(4)
	ds_write_b128 v48, v[30:33]
	v_mov_b32_e32 v37, v1
	v_lshlrev_b32_e32 v7, 1, v38
	v_and_b32_e32 v9, 0x118, v42
	s_movk_i32 s3, 0xf0
	s_mul_i32 s5, s2, 0x5800
	v_or_b32_e32 v44, 32, v0
	v_or_b32_e32 v45, 64, v0
	v_or_b32_e32 v2, 0x60, v0
	v_or_b32_e32 v3, 0x80, v0
	v_or_b32_e32 v4, 0xa0, v0
	v_or_b32_e32 v5, 0xc0, v0
	v_or_b32_e32 v6, 0xe0, v0
	v_and_b32_e32 v8, 0xc0, v39
	v_bitop3_b32 v222, v0, v39, s3 bitop3:0x78
	v_bitop3_b32 v223, v0, v214, v43 bitop3:0xde
	v_and_or_b32 v0, v7, 32, v9
	s_bfe_u32 s3, s22, 0x40002
	s_add_i32 s2, s5, 0x2c00
	v_add3_u32 v231, v8, 0, v0
	s_mul_i32 s3, s3, 0x160000
	v_mov_b32_e32 v0, s2
	s_or_b32 s4, s3, s36
	v_mad_u32_u24 v0, v40, s8, v0
	v_readlane_b32 s2, v255, 32
	v_or_b32_e32 v0, v0, v57
	s_add_u32 s2, s2, s4
	v_readlane_b32 s3, v255, 33
	v_bitop3_b32 v226, v2, v214, v43 bitop3:0xde
	v_lshlrev_b32_e32 v0, 1, v0
	s_addc_u32 s3, s3, 0
	v_mov_b32_e32 v2, s5
	v_lshl_add_u64 v[196:197], s[2:3], 0, v[0:1]
	v_mad_u32_u24 v0, v40, s8, v2
	v_or_b32_e32 v0, v0, v49
	v_lshlrev_b32_e32 v0, 1, v0
	v_lshl_add_u64 v[198:199], s[2:3], 0, v[0:1]
	v_mad_u32_u24 v0, v41, s8, v2
	v_readlane_b32 s2, v255, 34
	v_or_b32_e32 v0, v46, v0
	s_add_u32 s2, s2, s4
	v_readlane_b32 s3, v255, 36
	v_lshlrev_b32_e32 v0, 1, v0
	s_addc_u32 s3, s3, 0
	s_waitcnt vmcnt(0)
	v_lshl_add_u64 v[200:201], s[2:3], 0, v[0:1]
	v_or_b32_e32 v0, 0x80, v0
	v_mov_b32_e32 v16, v1
	v_mov_b32_e32 v17, v1
	v_bitop3_b32 v224, v44, v214, v43 bitop3:0xde
	v_bitop3_b32 v225, v45, v214, v43 bitop3:0xde
	v_bitop3_b32 v227, v3, v214, v43 bitop3:0xde
	v_bitop3_b32 v228, v4, v214, v43 bitop3:0xde
	v_bitop3_b32 v229, v5, v214, v43 bitop3:0xde
	v_bitop3_b32 v230, v6, v214, v43 bitop3:0xde
	v_lshl_add_u64 v[202:203], s[2:3], 0, v[0:1]
	v_mov_b32_e32 v0, v1
	v_mov_b32_e32 v2, v1
	v_mov_b32_e32 v3, v1
	v_mov_b32_e32 v4, v1
	v_mov_b32_e32 v5, v1
	v_mov_b32_e32 v6, v1
	v_mov_b32_e32 v7, v1
	v_mov_b32_e32 v8, v1
	v_mov_b32_e32 v9, v1
	v_mov_b32_e32 v10, v1
	v_mov_b32_e32 v11, v1
	v_mov_b32_e32 v12, v1
	v_mov_b32_e32 v13, v1
	v_mov_b32_e32 v14, v1
	v_mov_b32_e32 v15, v1
	v_mov_b64_e32 v[80:81], v[16:17]
	v_mov_b64_e32 v[48:49], v[16:17]
	v_mov_b64_e32 v[32:33], v[16:17]
	v_mov_b64_e32 v[128:129], v[16:17]
	v_mov_b64_e32 v[112:113], v[16:17]
	v_mov_b64_e32 v[96:97], v[16:17]
	v_mov_b64_e32 v[64:65], v[16:17]
	s_mov_b32 s36, 0
	v_mov_b32_e32 v233, 0
	s_mov_b64 s[4:5], 0
	s_mov_b64 s[8:9], -1
	s_mov_b64 s[6:7], 0
	v_mov_b64_e32 v[78:79], v[14:15]
	v_mov_b64_e32 v[76:77], v[12:13]
	v_mov_b64_e32 v[74:75], v[10:11]
	v_mov_b64_e32 v[72:73], v[8:9]
	v_mov_b64_e32 v[70:71], v[6:7]
	v_mov_b64_e32 v[68:69], v[4:5]
	v_mov_b64_e32 v[66:67], v[2:3]
	v_mov_b64_e32 v[46:47], v[14:15]
	v_mov_b64_e32 v[44:45], v[12:13]
	v_mov_b64_e32 v[42:43], v[10:11]
	v_mov_b64_e32 v[40:41], v[8:9]
	v_mov_b64_e32 v[38:39], v[6:7]
	v_mov_b64_e32 v[36:37], v[4:5]
	v_mov_b64_e32 v[34:35], v[2:3]
	v_mov_b64_e32 v[30:31], v[14:15]
	v_mov_b64_e32 v[28:29], v[12:13]
	v_mov_b64_e32 v[26:27], v[10:11]
	v_mov_b64_e32 v[24:25], v[8:9]
	v_mov_b64_e32 v[22:23], v[6:7]
	v_mov_b64_e32 v[20:21], v[4:5]
	v_mov_b64_e32 v[18:19], v[2:3]
	v_mov_b64_e32 v[126:127], v[14:15]
	v_mov_b64_e32 v[124:125], v[12:13]
	v_mov_b64_e32 v[122:123], v[10:11]
	v_mov_b64_e32 v[120:121], v[8:9]
	v_mov_b64_e32 v[118:119], v[6:7]
	v_mov_b64_e32 v[116:117], v[4:5]
	v_mov_b64_e32 v[114:115], v[2:3]
	v_mov_b64_e32 v[110:111], v[14:15]
	v_mov_b64_e32 v[108:109], v[12:13]
	v_mov_b64_e32 v[106:107], v[10:11]
	v_mov_b64_e32 v[104:105], v[8:9]
	v_mov_b64_e32 v[102:103], v[6:7]
	v_mov_b64_e32 v[100:101], v[4:5]
	v_mov_b64_e32 v[98:99], v[2:3]
	v_mov_b64_e32 v[94:95], v[14:15]
	v_mov_b64_e32 v[92:93], v[12:13]
	v_mov_b64_e32 v[90:91], v[10:11]
	v_mov_b64_e32 v[88:89], v[8:9]
	v_mov_b64_e32 v[86:87], v[6:7]
	v_mov_b64_e32 v[84:85], v[4:5]
	v_mov_b64_e32 v[82:83], v[2:3]
	v_mov_b64_e32 v[62:63], v[14:15]
	v_mov_b64_e32 v[60:61], v[12:13]
	v_mov_b64_e32 v[58:59], v[10:11]
	v_mov_b64_e32 v[56:57], v[8:9]
	v_mov_b64_e32 v[54:55], v[6:7]
	v_mov_b64_e32 v[52:53], v[4:5]
	v_mov_b64_e32 v[50:51], v[2:3]
	v_mov_b32_e32 v232, 0
	v_mov_b64_e32 v[204:205], v[0:1]
	s_waitcnt vmcnt(0) lgkmcnt(0)
	s_barrier
	s_branch .LBB0_751

.LBB0_840:
	s_or_b32 s16, s2, s29
	s_lshl_b32 s2, s16, 14
	s_or_b32 s36, s2, s1
	s_lshl_b64 s[2:3], s[36:37], 2
	s_waitcnt lgkmcnt(0)
	s_add_u32 s4, s8, s2
	s_addc_u32 s5, s9, s3
	s_add_u32 s6, s12, s2
	s_addc_u32 s7, s13, s3
	global_load_dword v38, v141, s[4:5]
	global_load_dword v34, v141, s[4:5] offset:256
	global_load_dword v39, v141, s[4:5] offset:512
	global_load_dword v35, v141, s[4:5] offset:768
	global_load_dword v40, v141, s[4:5] offset:1024
	global_load_dword v36, v141, s[4:5] offset:1280
	global_load_dword v58, v141, s[4:5] offset:1536
	global_load_dword v37, v141, s[4:5] offset:1792
	global_load_dword v64, v141, s[6:7]
	global_load_dword v63, v141, s[6:7] offset:256
	global_load_dword v62, v141, s[6:7] offset:512
	global_load_dword v61, v141, s[6:7] offset:768
	global_load_dword v60, v141, s[6:7] offset:1024
	global_load_dword v59, v141, s[6:7] offset:1280
	global_load_dword v57, v141, s[6:7] offset:1536
	global_load_dword v41, v141, s[6:7] offset:1792
	global_load_dword v42, v142, s[4:5]
	global_load_dword v55, v142, s[6:7]
	global_load_dword v56, v143, s[4:5]
	global_load_dword v46, v143, s[6:7]
	global_load_dword v43, v144, s[4:5]
	global_load_dword v53, v144, s[6:7]
	global_load_dword v54, v145, s[4:5]
	global_load_dword v47, v145, s[6:7]
	global_load_dword v44, v146, s[4:5]
	global_load_dword v51, v146, s[6:7]
	global_load_dword v52, v147, s[4:5]
	global_load_dword v48, v147, s[6:7]
	global_load_dword v45, v148, s[4:5]
	global_load_dword v49, v148, s[6:7]
	global_load_dword v50, v149, s[4:5]
	global_load_dword v33, v149, s[6:7]
	global_load_dword v31, v150, s[4:5]
	global_load_dword v30, v150, s[6:7]
	global_load_dword v32, v151, s[4:5]
	global_load_dword v29, v151, s[6:7]
	global_load_dword v27, v152, s[4:5]
	global_load_dword v26, v152, s[6:7]
	global_load_dword v28, v153, s[4:5]
	global_load_dword v25, v153, s[6:7]
	global_load_dword v23, v154, s[4:5]
	global_load_dword v22, v154, s[6:7]
	global_load_dword v24, v155, s[4:5]
	global_load_dword v21, v155, s[6:7]
	global_load_dword v16, v156, s[4:5]
	global_load_dword v15, v156, s[6:7]
	global_load_dword v17, v157, s[4:5]
	global_load_dword v14, v157, s[6:7]
	global_load_dword v12, v158, s[4:5]
	global_load_dword v11, v158, s[6:7]
	global_load_dword v13, v159, s[4:5]
	global_load_dword v10, v159, s[6:7]
	global_load_dword v8, v160, s[4:5]
	global_load_dword v7, v160, s[6:7]
	global_load_dword v9, v161, s[4:5]
	global_load_dword v6, v161, s[6:7]
	global_load_dword v4, v162, s[4:5]
	global_load_dword v3, v162, s[6:7]
	global_load_dword v5, v163, s[4:5]
	global_load_dword v2, v163, s[6:7]
	global_load_dword v19, v164, s[4:5]
	global_load_dword v18, v164, s[6:7]
	s_load_dwordx2 s[2:3], s[18:19], 0x70
	v_lshl_or_b32 v0, s16, 8, v132
	v_lshlrev_b64 v[68:69], 2, v[0:1]
	v_lshl_add_u64 v[78:79], s[10:11], 0, v[68:69]
	s_waitcnt lgkmcnt(0)
	v_lshl_add_u64 v[66:67], s[2:3], 0, v[68:69]
	global_load_dword v67, v[66:67], off
	s_nop 0
	global_load_dword v20, v165, s[4:5]
	global_load_dword v65, v165, s[6:7]
	v_lshl_add_u64 v[68:69], s[14:15], 0, v[68:69]
	global_load_dword v199, v[78:79], off
	global_load_dword v200, v[68:69], off
	s_mov_b32 m0, s55
	s_nop 0
	global_load_lds_dwordx4 v[70:71], off
	s_mov_b32 m0, s57
	s_nop 0
	global_load_lds_dwordx4 v[72:73], off
	s_mov_b32 m0, s63
	s_nop 0
	global_load_lds_dwordx4 v[74:75], off
	s_mov_b32 m0, s65
	s_nop 0
	global_load_lds_dwordx4 v[76:77], off
	s_waitcnt vmcnt(8)
	v_mul_f32_e64 v0, |v67|, s84
	v_exp_f32_e32 v0, v0
	s_nop 0
	v_cmp_ngt_f32_e32 vcc, s69, v0
	s_and_saveexec_b64 s[2:3], vcc
	s_xor_b64 s[6:7], exec, s[2:3]
	s_cbranch_execz .LBB0_842
	v_add_f32_e32 v0, 1.0, v0
	v_cmp_gt_f32_e32 vcc, s25, v0
	s_nop 1
	v_cndmask_b32_e64 v66, 0, 32, vcc
	v_ldexp_f32 v0, v0, v66
	v_log_f32_e32 v0, v0
	s_nop 0
	v_mul_f32_e32 v66, 0x3f317217, v0
	v_fma_f32 v66, v0, s76, -v66
	v_fmac_f32_e32 v66, 0x3377d1cf, v0
	v_fmac_f32_e32 v66, 0x3f317217, v0
	v_cmp_lt_f32_e64 s[4:5], |v0|, s77
	s_nop 1
	v_cndmask_b32_e64 v0, v0, v66, s[4:5]
	v_cndmask_b32_e32 v66, 0, v250, vcc
	v_sub_f32_e32 v68, v0, v66
.LBB0_842:
	s_andn2_saveexec_b64 s[4:5], s[6:7]
	v_fma_f32 v66, v0, -0.5, 1.0
	v_mul_f32_e32 v68, v0, v66
	s_or_b64 exec, exec, s[4:5]
	s_add_i32 s4, s55, 0
	s_add_i32 s5, s57, 0
	s_add_i32 s6, s63, 0
	s_add_i32 s7, s65, 0
	s_and_b64 s[2:3], s[46:47], exec
	s_cselect_b32 s2, 0, 0x700
	v_mov_b32_e32 v66, v122
	s_or_b32 s2, s2, s53
	s_add_i32 s3, s2, s54
	v_ashrrev_i32_e32 v69, 3, v66
	v_lshrrev_b32_e32 v0, 1, v69
	v_add_u32_e32 v78, s3, v69
	v_xor_b32_e32 v0, v0, v66
	v_ashrrev_i32_e32 v79, 31, v78
	v_lshlrev_b64 v[78:79], 9, v[78:79]
	v_lshlrev_b32_e32 v0, 4, v0
	s_waitcnt vmcnt(0)
	v_lshl_add_u64 v[78:79], s[38:39], 0, v[78:79]
	v_and_b32_e32 v0, 0x70, v0
	s_waitcnt lgkmcnt(0)
	s_barrier
	v_lshl_add_u64 v[78:79], v[78:79], 0, v[0:1]
	s_add_i32 m0, s4, 0x8000
	v_add_u32_e32 v0, s56, v69
	s_add_i32 s3, s2, s56
	global_load_lds_dwordx4 v[78:79], off
	v_lshrrev_b32_e32 v0, 1, v0
	v_add_u32_e32 v78, s3, v69
	v_xor_b32_e32 v0, v0, v66
	v_ashrrev_i32_e32 v79, 31, v78
	v_lshlrev_b64 v[78:79], 9, v[78:79]
	v_lshlrev_b32_e32 v0, 4, v0
	v_lshl_add_u64 v[78:79], s[38:39], 0, v[78:79]
	v_and_b32_e32 v0, 0x70, v0
	v_lshl_add_u64 v[78:79], v[78:79], 0, v[0:1]
	s_add_i32 m0, s5, 0x8000
	v_add_u32_e32 v0, s62, v69
	s_add_i32 s3, s2, s62
	global_load_lds_dwordx4 v[78:79], off
	v_lshrrev_b32_e32 v0, 1, v0
	v_add_u32_e32 v78, s3, v69
	v_xor_b32_e32 v0, v0, v66
	v_ashrrev_i32_e32 v79, 31, v78
	v_lshlrev_b64 v[78:79], 9, v[78:79]
	v_lshlrev_b32_e32 v0, 4, v0
	v_lshl_add_u64 v[78:79], s[38:39], 0, v[78:79]
	v_and_b32_e32 v0, 0x70, v0
	v_lshl_add_u64 v[78:79], v[78:79], 0, v[0:1]
	s_add_i32 m0, s6, 0x8000
	v_add_u32_e32 v0, s64, v69
	s_add_i32 s2, s2, s64
	global_load_lds_dwordx4 v[78:79], off
	v_lshrrev_b32_e32 v0, 1, v0
	v_add_u32_e32 v78, s2, v69
	v_xor_b32_e32 v0, v0, v66
	v_ashrrev_i32_e32 v79, 31, v78
	v_lshlrev_b64 v[78:79], 9, v[78:79]
	v_lshlrev_b32_e32 v0, 4, v0
	v_lshl_add_u64 v[78:79], s[38:39], 0, v[78:79]
	v_and_b32_e32 v0, 0x70, v0
	v_lshl_add_u64 v[78:79], v[78:79], 0, v[0:1]
	s_add_i32 m0, s7, 0x8000
	s_and_b64 s[2:3], s[44:45], s[82:83]
	global_load_lds_dwordx4 v[78:79], off
	v_cndmask_b32_e64 v0, 0, 1, s[2:3]
	v_cmp_ne_u32_e64 s[6:7], 1, v0
	s_andn2_b64 vcc, exec, s[2:3]
	s_cbranch_vccnz .LBB0_846
	v_ashrrev_i32_e32 v0, 2, v66
	v_add_u32_e32 v69, s31, v0
	v_add_u32_e32 v80, s54, v69
	v_mov_b64_e32 v[82:83], s[20:21]
	v_lshlrev_b32_e32 v0, 4, v66
	v_mad_i64_i32 v[84:85], s[2:3], v80, s72, v[82:83]
	s_lshl_b32 s36, s0, 1
	v_and_b32_e32 v0, 48, v0
	v_lshl_add_u64 v[84:85], v[84:85], 0, s[36:37]
	v_ashrrev_i32_e32 v81, 31, v80
	v_lshl_add_u64 v[84:85], v[84:85], 0, v[0:1]
	s_add_i32 s4, 0, 0x18000
	v_lshl_add_u64 v[78:79], s[40:41], 0, v[0:1]
	v_lshl_add_u64 v[84:85], v[84:85], 0, s[94:95]
	s_add_i32 m0, s4, s66
	v_lshlrev_b64 v[80:81], 9, v[80:81]
	s_add_i32 s5, 0, 0x1c000
	global_load_lds_dwordx4 v[84:85], off
	v_lshl_add_u64 v[80:81], v[78:79], 0, v[80:81]
	s_add_i32 m0, s5, s66
	s_nop 0
	global_load_lds_dwordx4 v[80:81], off
	v_add_u32_e32 v80, s67, v69
	v_mad_i64_i32 v[82:83], s[2:3], v80, s72, v[82:83]
	v_lshl_add_u64 v[82:83], v[82:83], 0, s[36:37]
	v_ashrrev_i32_e32 v81, 31, v80
	v_lshl_add_u64 v[82:83], v[82:83], 0, v[0:1]
	v_lshl_add_u64 v[82:83], v[82:83], 0, s[94:95]
	s_add_i32 m0, s4, s68
	v_lshlrev_b64 v[80:81], 9, v[80:81]
	global_load_lds_dwordx4 v[82:83], off
	v_lshl_add_u64 v[78:79], v[78:79], 0, v[80:81]
	s_add_i32 m0, s5, s68
	s_nop 0
	global_load_lds_dwordx4 v[78:79], off
